# PG fused epilogue: same load batching as PD (gain vector once, residual half-rows paired)
# speedup vs baseline: 1.0141x; 1.0082x over previous
; #define LAS __attribute__((address_space(3)))
;     __device__ __forceinline__ void exchange(int e, float (&sv)[2][4], float (&rv)[2][4], const Unit& u, int wr, int wc, int fr, int fq, LAS unsigned char* lds, int wid, int lane) const {
;     ...
;             for (int m = 0; m < 4; ++m) rv[ai][m] = Sx[ai * HALF + wr * 64 + m * 16 + fr];
;     }
;     __device__ __forceinline__ void fused(f32x4 (&acc)[2][2][4][2], const Unit& u, int wr, int wc, int fr, int fq, LAS unsigned char* lds, int wid, int lane) const {
;         bf16_t* hb = (bf16_t*)(ws + WS_HB);
;         const int row0 = u.pm * BM + wr * 64 + fr, col0 = u.pn * BM + wc * 32 + 8 * fq;
;         float sv[2][4], rv[2][4];
; #pragma unroll
;         for (int ai = 0; ai < 2; ++ai)
; #pragma unroll
;             for (int m = 0; m < 4; ++m) {
;                 float q = 0.f;
; #pragma unroll
;                 for (int bj = 0; bj < 2; ++bj)
; #pragma unroll
;                     for (int n = 0; n < 2; ++n) { const f32x4 x = acc[ai][bj][m][n]; q += (x[0] * x[0] + x[1] * x[1]) + (x[2] * x[2] + x[3] * x[3]); }
;                 sv[ai][m] = q;
;             }
;         exchange(0, sv, rv, u, wr, wc, fr, fq, lds, wid, lane);
;         float dep = 0.f;
; #pragma unroll
;         for (int ai = 0; ai < 2; ++ai)
; #pragma unroll
;             for (int m = 0; m < 4; ++m) {
;                 const bf16_t* hrow = hb + (size_t)(row0 + ai * HALF + m * 16) * DM + col0;
;                 asm volatile("" : "+v"(hrow) : "v"(dep));
;                 const float r1 = rv[ai][m];
;                 float q = 0.f;
; #pragma unroll
;                 for (int bj = 0; bj < 2; ++bj) {
;                     const u32x4 hv = *(const u32x4*)(hrow + bj * HALF);
;                     const f32x4 h0 = (f32x4){__uint_as_float(hv.x << 16), __uint_as_float(hv.x & 0xffff0000u), __uint_as_float(hv.y << 16), __uint_as_float(hv.y & 0xffff0000u)};
;                     const f32x4 h1 = (f32x4){__uint_as_float(hv.z << 16), __uint_as_float(hv.z & 0xffff0000u), __uint_as_float(hv.w << 16), __uint_as_float(hv.w & 0xffff0000u)};
;                     const f32x4 gg0 = *(const f32x4*)(gpost + col0 + bj * HALF), gg1 = *(const f32x4*)(gpost + col0 + bj * HALF + 4);
;                     f32x4 x0 = h0 + acc[ai][bj][m][0] * r1 * gg0, x1 = h1 + acc[ai][bj][m][1] * r1 * gg1;
.LBB0_1668:
	s_or_b64 exec, exec, s[44:45]
	v_lshl_add_u32 v146, s36, 8, v1
	v_lshl_or_b32 v154, s34, 8, v188
	v_ashrrev_i32_e32 v155, 31, v154
	v_ashrrev_i32_e32 v147, 31, v146
	v_lshl_add_u64 v[164:165], v[154:155], 1, s[26:27]
	v_lshlrev_b64 v[148:149], 11, v[146:147]
	v_lshl_add_u64 v[148:149], v[164:165], 0, v[148:149]
	s_waitcnt vmcnt(0) lgkmcnt(0)
	s_barrier
	v_mov_b64_e32 v[162:163], v[148:149]
	ds_read2_b32 v[160:161], v194 offset1:16
	ds_read2_b32 v[170:171], v194 offset0:32 offset1:48
	ds_read2_b32 v[174:175], v194 offset0:128 offset1:144
	ds_read2_b32 v[158:159], v194 offset0:160 offset1:176
	flat_load_dwordx4 v[150:153], v[162:163]
	flat_load_dwordx4 v[232:235], v[162:163] offset:256
	v_lshl_add_u64 v[156:157], v[154:155], 2, s[18:19]
	global_load_dwordx4 v[236:239], v[156:157], off
	global_load_dwordx4 v[240:243], v[156:157], off offset:16
	global_load_dwordx4 v[244:247], v[156:157], off offset:512
	global_load_dwordx4 v[248:251], v[156:157], off offset:528
	s_waitcnt lgkmcnt(0)
	v_pk_mul_f32 v[32:33], v[32:33], v[160:161] op_sel_hi:[1,0]
	v_pk_mul_f32 v[30:31], v[30:31], v[160:161] op_sel_hi:[1,0]
	v_pk_mul_f32 v[28:29], v[28:29], v[160:161] op_sel_hi:[1,0]
	v_pk_mul_f32 v[26:27], v[26:27], v[160:161] op_sel_hi:[1,0]
	v_pk_mul_f32 v[42:43], v[42:43], v[160:161] op_sel_hi:[1,0]
	v_pk_mul_f32 v[44:45], v[44:45], v[160:161] op_sel_hi:[1,0]
	v_pk_mul_f32 v[48:49], v[48:49], v[160:161] op_sel_hi:[1,0]
	v_pk_mul_f32 v[46:47], v[46:47], v[160:161] op_sel_hi:[1,0]
	v_mov_b32_e32 v196, v161
	v_pk_mul_f32 v[60:61], v[60:61], v[196:197] op_sel_hi:[1,0]
	v_pk_mul_f32 v[58:59], v[58:59], v[196:197] op_sel_hi:[1,0]
	v_pk_mul_f32 v[64:65], v[64:65], v[196:197] op_sel_hi:[1,0]
	v_pk_mul_f32 v[62:63], v[62:63], v[196:197] op_sel_hi:[1,0]
	v_pk_mul_f32 v[74:75], v[74:75], v[196:197] op_sel_hi:[1,0]
	v_pk_mul_f32 v[76:77], v[76:77], v[196:197] op_sel_hi:[1,0]
	v_pk_mul_f32 v[80:81], v[80:81], v[196:197] op_sel_hi:[1,0]
	v_pk_mul_f32 v[78:79], v[78:79], v[196:197] op_sel_hi:[1,0]
	v_pk_mul_f32 v[90:91], v[90:91], v[170:171] op_sel_hi:[1,0]
	v_pk_mul_f32 v[92:93], v[92:93], v[170:171] op_sel_hi:[1,0]
	v_pk_mul_f32 v[96:97], v[96:97], v[170:171] op_sel_hi:[1,0]
	v_pk_mul_f32 v[94:95], v[94:95], v[170:171] op_sel_hi:[1,0]
	v_pk_mul_f32 v[106:107], v[106:107], v[170:171] op_sel_hi:[1,0]
	v_pk_mul_f32 v[108:109], v[108:109], v[170:171] op_sel_hi:[1,0]
	v_pk_mul_f32 v[112:113], v[112:113], v[170:171] op_sel_hi:[1,0]
	v_pk_mul_f32 v[110:111], v[110:111], v[170:171] op_sel_hi:[1,0]
	v_mov_b32_e32 v204, v171
	v_pk_mul_f32 v[116:117], v[116:117], v[204:205] op_sel_hi:[1,0]
	v_pk_mul_f32 v[114:115], v[114:115], v[204:205] op_sel_hi:[1,0]
	v_pk_mul_f32 v[120:121], v[120:121], v[204:205] op_sel_hi:[1,0]
	v_pk_mul_f32 v[118:119], v[118:119], v[204:205] op_sel_hi:[1,0]
	v_pk_mul_f32 v[126:127], v[126:127], v[204:205] op_sel_hi:[1,0]
	v_pk_mul_f32 v[128:129], v[128:129], v[204:205] op_sel_hi:[1,0]
	v_pk_mul_f32 v[124:125], v[124:125], v[204:205] op_sel_hi:[1,0]
	v_pk_mul_f32 v[122:123], v[122:123], v[204:205] op_sel_hi:[1,0]
	v_pk_mul_f32 v[102:103], v[102:103], v[174:175] op_sel_hi:[1,0]
	v_pk_mul_f32 v[104:105], v[104:105], v[174:175] op_sel_hi:[1,0]
	v_pk_mul_f32 v[100:101], v[100:101], v[174:175] op_sel_hi:[1,0]
	v_pk_mul_f32 v[98:99], v[98:99], v[174:175] op_sel_hi:[1,0]
	v_pk_mul_f32 v[86:87], v[86:87], v[174:175] op_sel_hi:[1,0]
	v_pk_mul_f32 v[88:89], v[88:89], v[174:175] op_sel_hi:[1,0]
	v_pk_mul_f32 v[84:85], v[84:85], v[174:175] op_sel_hi:[1,0]
	v_pk_mul_f32 v[82:83], v[82:83], v[174:175] op_sel_hi:[1,0]
	v_mov_b32_e32 v174, v175
	v_pk_mul_f32 v[66:67], v[66:67], v[174:175] op_sel_hi:[1,0]
	v_pk_mul_f32 v[72:73], v[72:73], v[174:175] op_sel_hi:[1,0]
	v_pk_mul_f32 v[70:71], v[70:71], v[174:175] op_sel_hi:[1,0]
	v_pk_mul_f32 v[68:69], v[68:69], v[174:175] op_sel_hi:[1,0]
	v_pk_mul_f32 v[54:55], v[54:55], v[174:175] op_sel_hi:[1,0]
	v_pk_mul_f32 v[56:57], v[56:57], v[174:175] op_sel_hi:[1,0]
	v_pk_mul_f32 v[50:51], v[50:51], v[174:175] op_sel_hi:[1,0]
	v_pk_mul_f32 v[52:53], v[52:53], v[174:175] op_sel_hi:[1,0]
	v_pk_mul_f32 v[38:39], v[38:39], v[158:159] op_sel_hi:[1,0]
	v_pk_mul_f32 v[40:41], v[40:41], v[158:159] op_sel_hi:[1,0]
	v_pk_mul_f32 v[36:37], v[36:37], v[158:159] op_sel_hi:[1,0]
	v_pk_mul_f32 v[34:35], v[34:35], v[158:159] op_sel_hi:[1,0]
	v_pk_mul_f32 v[22:23], v[22:23], v[158:159] op_sel_hi:[1,0]
	v_pk_mul_f32 v[24:25], v[24:25], v[158:159] op_sel_hi:[1,0]
	v_pk_mul_f32 v[20:21], v[20:21], v[158:159] op_sel_hi:[1,0]
	v_pk_mul_f32 v[18:19], v[18:19], v[158:159] op_sel_hi:[1,0]
	v_mov_b32_e32 v218, v159
	v_pk_mul_f32 v[12:13], v[12:13], v[218:219] op_sel_hi:[1,0]
	v_pk_mul_f32 v[10:11], v[10:11], v[218:219] op_sel_hi:[1,0]
	v_pk_mul_f32 v[16:17], v[16:17], v[218:219] op_sel_hi:[1,0]
	v_pk_mul_f32 v[14:15], v[14:15], v[218:219] op_sel_hi:[1,0]
	v_pk_mul_f32 v[8:9], v[8:9], v[218:219] op_sel_hi:[1,0]
	v_pk_mul_f32 v[6:7], v[6:7], v[218:219] op_sel_hi:[1,0]
	v_pk_mul_f32 v[4:5], v[4:5], v[218:219] op_sel_hi:[1,0]
	v_pk_mul_f32 v[2:3], v[2:3], v[218:219] op_sel_hi:[1,0]
	s_andn2_b64 vcc, exec, s[28:29]
	s_waitcnt vmcnt(0)
	v_lshlrev_b32_e32 v172, 16, v150
	v_and_b32_e32 v173, 0xffff0000, v150
	v_lshlrev_b32_e32 v176, 16, v151
	v_and_b32_e32 v177, 0xffff0000, v151
	v_lshlrev_b32_e32 v178, 16, v152
	v_and_b32_e32 v179, 0xffff0000, v152
	v_lshlrev_b32_e32 v182, 16, v153
	v_and_b32_e32 v183, 0xffff0000, v153
	v_mov_b64_e32 v[150:151], v[240:241]
	v_mov_b64_e32 v[152:153], v[242:243]
	v_mov_b64_e32 v[166:167], v[236:237]
	v_mov_b64_e32 v[168:169], v[238:239]
	s_waitcnt vmcnt(1)
;     __device__ __forceinline__ void fused(f32x4 (&acc)[2][2][4][2], const Unit& u, int wr, int wc, int fr, int fq, LAS unsigned char* lds, int wid, int lane) const {
;     ...
; #pragma unroll
;             for (int m = 0; m < 4; ++m) {
;                 const bf16_t* hrow = hb + (size_t)(row0 + ai * HALF + m * 16) * DM + col0;
;                 asm volatile("" : "+v"(hrow) : "v"(dep));
;                 const float r1 = rv[ai][m];
;                 float q = 0.f;
; #pragma unroll
;                 for (int bj = 0; bj < 2; ++bj) {
;                     const u32x4 hv = *(const u32x4*)(hrow + bj * HALF);
;                     const f32x4 h0 = (f32x4){__uint_as_float(hv.x << 16), __uint_as_float(hv.x & 0xffff0000u), __uint_as_float(hv.y << 16), __uint_as_float(hv.y & 0xffff0000u)};
;                     const f32x4 h1 = (f32x4){__uint_as_float(hv.z << 16), __uint_as_float(hv.z & 0xffff0000u), __uint_as_float(hv.w << 16), __uint_as_float(hv.w & 0xffff0000u)};
;                     const f32x4 gg0 = *(const f32x4*)(gpost + col0 + bj * HALF), gg1 = *(const f32x4*)(gpost + col0 + bj * HALF + 4);
;                     f32x4 x0 = h0 + acc[ai][bj][m][0] * r1 * gg0, x1 = h1 + acc[ai][bj][m][1] * r1 * gg1;
;                     acc[ai][bj][m][0] = x0; acc[ai][bj][m][1] = x1;
;                     q += ((x0[0] * x0[0] + x0[1] * x0[1]) + (x0[2] * x0[2] + x0[3] * x0[3])) + ((x1[0] * x1[0] + x1[1] * x1[1]) + (x1[2] * x1[2] + x1[3] * x1[3]));
	v_pk_fma_f32 v[32:33], v[32:33], v[152:153], v[182:183]
	v_pk_fma_f32 v[30:31], v[30:31], v[150:151], v[178:179]
	v_mov_b64_e32 v[150:151], v[232:233]
	v_mov_b64_e32 v[152:153], v[234:235]
	s_waitcnt vmcnt(0)
	v_pk_fma_f32 v[28:29], v[28:29], v[168:169], v[176:177]
	v_pk_fma_f32 v[26:27], v[26:27], v[166:167], v[172:173]
	s_waitcnt lgkmcnt(0)
	v_lshlrev_b32_e32 v162, 16, v150
	v_and_b32_e32 v163, 0xffff0000, v150
	v_lshlrev_b32_e32 v172, 16, v151
	v_and_b32_e32 v173, 0xffff0000, v151
	v_lshlrev_b32_e32 v176, 16, v152
	v_and_b32_e32 v177, 0xffff0000, v152
	v_lshlrev_b32_e32 v178, 16, v153
	v_and_b32_e32 v179, 0xffff0000, v153
	v_mov_b64_e32 v[150:151], v[248:249]
	v_mov_b64_e32 v[152:153], v[250:251]
	v_mov_b64_e32 v[166:167], v[244:245]
	v_mov_b64_e32 v[168:169], v[246:247]
	s_waitcnt vmcnt(1)
	v_pk_fma_f32 v[48:49], v[48:49], v[152:153], v[178:179]
	s_waitcnt vmcnt(0)
	v_pk_fma_f32 v[42:43], v[42:43], v[166:167], v[162:163]
	v_pk_fma_f32 v[44:45], v[44:45], v[168:169], v[172:173]
	v_mov_b32_e32 v152, v27
	v_mov_b32_e32 v153, v43
	v_pk_fma_f32 v[46:47], v[46:47], v[150:151], v[176:177]
	v_mov_b32_e32 v150, v26
	v_mov_b32_e32 v151, v42
	v_pk_mul_f32 v[152:153], v[152:153], v[152:153]
	v_mov_b32_e32 v162, v29
	v_mov_b32_e32 v163, v45
	v_pk_fma_f32 v[150:151], v[150:151], v[150:151], v[152:153]
	v_mov_b32_e32 v152, v28
	v_mov_b32_e32 v153, v44
	v_pk_mul_f32 v[162:163], v[162:163], v[162:163]
	v_mov_b32_e32 v166, v33
	v_pk_fma_f32 v[152:153], v[152:153], v[152:153], v[162:163]
	v_mov_b32_e32 v162, v31
	v_mov_b32_e32 v163, v47
	v_pk_add_f32 v[150:151], v[150:151], v[152:153]
	v_mov_b32_e32 v152, v30
	v_mov_b32_e32 v153, v46
	v_pk_mul_f32 v[162:163], v[162:163], v[162:163]
	v_mov_b32_e32 v167, v49
	v_pk_fma_f32 v[152:153], v[152:153], v[152:153], v[162:163]
	v_mov_b32_e32 v162, v32
	v_mov_b32_e32 v163, v48
	v_pk_mul_f32 v[166:167], v[166:167], v[166:167]
	s_nop 0
	v_pk_fma_f32 v[162:163], v[162:163], v[162:163], v[166:167]
	s_nop 0
	v_pk_add_f32 v[152:153], v[152:153], v[162:163]
	s_nop 0
	v_pk_add_f32 v[150:151], v[150:151], v[152:153]
	s_nop 0
	v_add_f32_e32 v195, v150, v151
	v_or_b32_e32 v150, 16, v146
	v_ashrrev_i32_e32 v151, 31, v150
	v_lshlrev_b64 v[152:153], 11, v[150:151]
	v_lshl_add_u64 v[152:153], v[164:165], 0, v[152:153]
	v_mov_b64_e32 v[162:163], v[152:153]
	flat_load_dwordx4 v[166:169], v[162:163]
	flat_load_dwordx4 v[232:235], v[162:163] offset:256
	s_waitcnt vmcnt(0) lgkmcnt(0)
	v_lshlrev_b32_e32 v172, 16, v166
	v_and_b32_e32 v173, 0xffff0000, v166
	v_lshlrev_b32_e32 v182, 16, v167
	v_and_b32_e32 v183, 0xffff0000, v167
	v_lshlrev_b32_e32 v184, 16, v168
	v_and_b32_e32 v185, 0xffff0000, v168
	v_lshlrev_b32_e32 v186, 16, v169
	v_and_b32_e32 v187, 0xffff0000, v169
	v_mov_b64_e32 v[166:167], v[240:241]
	v_mov_b64_e32 v[168:169], v[242:243]
	v_mov_b64_e32 v[176:177], v[236:237]
	v_mov_b64_e32 v[178:179], v[238:239]
	s_waitcnt vmcnt(1)
	v_pk_fma_f32 v[64:65], v[64:65], v[168:169], v[186:187]
	v_mov_b64_e32 v[160:161], v[232:233]
	v_mov_b64_e32 v[162:163], v[234:235]
	s_waitcnt vmcnt(0)
	v_pk_fma_f32 v[60:61], v[60:61], v[178:179], v[182:183]
	v_pk_fma_f32 v[58:59], v[58:59], v[176:177], v[172:173]
	v_pk_fma_f32 v[62:63], v[62:63], v[166:167], v[184:185]
	s_waitcnt lgkmcnt(0)
	v_lshlrev_b32_e32 v172, 16, v160
	v_and_b32_e32 v173, 0xffff0000, v160
	v_lshlrev_b32_e32 v176, 16, v161
	v_and_b32_e32 v177, 0xffff0000, v161
	v_lshlrev_b32_e32 v178, 16, v162
	v_and_b32_e32 v179, 0xffff0000, v162
	v_lshlrev_b32_e32 v182, 16, v163
	v_and_b32_e32 v183, 0xffff0000, v163
	v_mov_b64_e32 v[160:161], v[248:249]
	v_mov_b64_e32 v[162:163], v[250:251]
	v_mov_b64_e32 v[166:167], v[244:245]
	v_mov_b64_e32 v[168:169], v[246:247]
	s_waitcnt vmcnt(1)
	v_pk_fma_f32 v[80:81], v[80:81], v[162:163], v[182:183]
	s_waitcnt vmcnt(0)
	v_pk_fma_f32 v[74:75], v[74:75], v[166:167], v[172:173]
	v_pk_fma_f32 v[76:77], v[76:77], v[168:169], v[176:177]
	v_mov_b32_e32 v162, v59
	v_mov_b32_e32 v163, v75
	v_pk_fma_f32 v[78:79], v[78:79], v[160:161], v[178:179]
	v_mov_b32_e32 v160, v58
	v_mov_b32_e32 v161, v74
	v_pk_mul_f32 v[162:163], v[162:163], v[162:163]
	v_mov_b32_e32 v166, v61
	v_mov_b32_e32 v167, v77
	v_pk_fma_f32 v[160:161], v[160:161], v[160:161], v[162:163]
	v_mov_b32_e32 v162, v60
	v_mov_b32_e32 v163, v76
	v_pk_mul_f32 v[166:167], v[166:167], v[166:167]
	v_mov_b32_e32 v168, v65
	v_pk_fma_f32 v[162:163], v[162:163], v[162:163], v[166:167]
	v_mov_b32_e32 v166, v63
	v_mov_b32_e32 v167, v79
	v_pk_add_f32 v[160:161], v[160:161], v[162:163]
	v_mov_b32_e32 v162, v62
	v_mov_b32_e32 v163, v78
	v_pk_mul_f32 v[166:167], v[166:167], v[166:167]
	v_mov_b32_e32 v169, v81
	v_pk_fma_f32 v[162:163], v[162:163], v[162:163], v[166:167]
	v_mov_b32_e32 v166, v64
	v_mov_b32_e32 v167, v80
	v_pk_mul_f32 v[168:169], v[168:169], v[168:169]
	s_nop 0
	v_pk_fma_f32 v[166:167], v[166:167], v[166:167], v[168:169]
	s_nop 0
	v_pk_add_f32 v[162:163], v[162:163], v[166:167]
	s_nop 0
	v_pk_add_f32 v[160:161], v[160:161], v[162:163]
	s_nop 0
	v_add_f32_e32 v196, v160, v161
	v_or_b32_e32 v160, 32, v146
	v_ashrrev_i32_e32 v161, 31, v160
	v_lshlrev_b64 v[162:163], 11, v[160:161]
	v_lshl_add_u64 v[162:163], v[164:165], 0, v[162:163]
	v_mov_b64_e32 v[166:167], v[162:163]
	flat_load_dwordx4 v[176:179], v[166:167]
	flat_load_dwordx4 v[232:235], v[166:167] offset:256
	s_waitcnt vmcnt(0) lgkmcnt(0)
	v_lshlrev_b32_e32 v168, 16, v176
	v_and_b32_e32 v169, 0xffff0000, v176
	v_lshlrev_b32_e32 v172, 16, v177
	v_and_b32_e32 v173, 0xffff0000, v177
	v_lshlrev_b32_e32 v186, 16, v178
	v_and_b32_e32 v187, 0xffff0000, v178
	v_lshlrev_b32_e32 v198, 16, v179
	v_and_b32_e32 v199, 0xffff0000, v179
	v_mov_b64_e32 v[176:177], v[240:241]
	v_mov_b64_e32 v[178:179], v[242:243]
	v_mov_b64_e32 v[182:183], v[236:237]
	v_mov_b64_e32 v[184:185], v[238:239]
	s_waitcnt vmcnt(1)
;     __device__ __forceinline__ void fused(f32x4 (&acc)[2][2][4][2], const Unit& u, int wr, int wc, int fr, int fq, LAS unsigned char* lds, int wid, int lane) const {
;     ...
; #pragma unroll
;             for (int m = 0; m < 4; ++m) {
;                 const bf16_t* hrow = hb + (size_t)(row0 + ai * HALF + m * 16) * DM + col0;
;                 asm volatile("" : "+v"(hrow) : "v"(dep));
;                 const float r1 = rv[ai][m];
;                 float q = 0.f;
; #pragma unroll
;                 for (int bj = 0; bj < 2; ++bj) {
;                     const u32x4 hv = *(const u32x4*)(hrow + bj * HALF);
;                     const f32x4 h0 = (f32x4){__uint_as_float(hv.x << 16), __uint_as_float(hv.x & 0xffff0000u), __uint_as_float(hv.y << 16), __uint_as_float(hv.y & 0xffff0000u)};
;                     const f32x4 h1 = (f32x4){__uint_as_float(hv.z << 16), __uint_as_float(hv.z & 0xffff0000u), __uint_as_float(hv.w << 16), __uint_as_float(hv.w & 0xffff0000u)};
;                     const f32x4 gg0 = *(const f32x4*)(gpost + col0 + bj * HALF), gg1 = *(const f32x4*)(gpost + col0 + bj * HALF + 4);
;                     f32x4 x0 = h0 + acc[ai][bj][m][0] * r1 * gg0, x1 = h1 + acc[ai][bj][m][1] * r1 * gg1;
;                     acc[ai][bj][m][0] = x0; acc[ai][bj][m][1] = x1;
;                     q += ((x0[0] * x0[0] + x0[1] * x0[1]) + (x0[2] * x0[2] + x0[3] * x0[3])) + ((x1[0] * x1[0] + x1[1] * x1[1]) + (x1[2] * x1[2] + x1[3] * x1[3]));
	v_pk_fma_f32 v[96:97], v[96:97], v[178:179], v[198:199]
	s_waitcnt vmcnt(0)
	v_pk_fma_f32 v[90:91], v[90:91], v[182:183], v[168:169]
	v_mov_b64_e32 v[166:167], v[232:233]
	v_mov_b64_e32 v[168:169], v[234:235]
	v_pk_fma_f32 v[92:93], v[92:93], v[184:185], v[172:173]
	v_pk_fma_f32 v[94:95], v[94:95], v[176:177], v[186:187]
	s_waitcnt vmcnt(0) lgkmcnt(0)
	v_lshlrev_b32_e32 v172, 16, v166
	v_and_b32_e32 v173, 0xffff0000, v166
	v_lshlrev_b32_e32 v182, 16, v167
	v_and_b32_e32 v183, 0xffff0000, v167
	v_lshlrev_b32_e32 v184, 16, v168
	v_and_b32_e32 v185, 0xffff0000, v168
	v_lshlrev_b32_e32 v186, 16, v169
	v_and_b32_e32 v187, 0xffff0000, v169
	v_mov_b64_e32 v[166:167], v[248:249]
	v_mov_b64_e32 v[168:169], v[250:251]
	v_mov_b64_e32 v[176:177], v[244:245]
	v_mov_b64_e32 v[178:179], v[246:247]
	s_waitcnt vmcnt(1)
	v_pk_fma_f32 v[112:113], v[112:113], v[168:169], v[186:187]
	s_waitcnt vmcnt(0)
	v_pk_fma_f32 v[106:107], v[106:107], v[176:177], v[172:173]
	v_pk_fma_f32 v[108:109], v[108:109], v[178:179], v[182:183]
	v_mov_b32_e32 v168, v91
	v_mov_b32_e32 v169, v107
	v_pk_fma_f32 v[110:111], v[110:111], v[166:167], v[184:185]
	v_mov_b32_e32 v166, v90
	v_mov_b32_e32 v167, v106
	v_pk_mul_f32 v[168:169], v[168:169], v[168:169]
	v_mov_b32_e32 v172, v93
	v_mov_b32_e32 v173, v109
	v_pk_fma_f32 v[166:167], v[166:167], v[166:167], v[168:169]
	v_mov_b32_e32 v168, v92
	v_mov_b32_e32 v169, v108
	v_pk_mul_f32 v[172:173], v[172:173], v[172:173]
	v_mov_b32_e32 v176, v97
	v_pk_fma_f32 v[168:169], v[168:169], v[168:169], v[172:173]
	v_mov_b32_e32 v172, v95
	v_mov_b32_e32 v173, v111
	v_pk_add_f32 v[166:167], v[166:167], v[168:169]
	v_mov_b32_e32 v168, v94
	v_mov_b32_e32 v169, v110
	v_pk_mul_f32 v[172:173], v[172:173], v[172:173]
	v_mov_b32_e32 v177, v113
	v_pk_fma_f32 v[168:169], v[168:169], v[168:169], v[172:173]
	v_mov_b32_e32 v172, v96
	v_mov_b32_e32 v173, v112
	v_pk_mul_f32 v[176:177], v[176:177], v[176:177]
	s_nop 0
	v_pk_fma_f32 v[172:173], v[172:173], v[172:173], v[176:177]
	s_nop 0
	v_pk_add_f32 v[168:169], v[168:169], v[172:173]
	s_nop 0
	v_pk_add_f32 v[166:167], v[166:167], v[168:169]
	s_nop 0
	v_add_f32_e32 v197, v166, v167
	v_or_b32_e32 v166, 48, v146
	v_ashrrev_i32_e32 v167, 31, v166
	v_lshlrev_b64 v[168:169], 11, v[166:167]
	v_lshl_add_u64 v[168:169], v[164:165], 0, v[168:169]
	v_mov_b64_e32 v[172:173], v[168:169]
	flat_load_dwordx4 v[176:179], v[172:173]
	flat_load_dwordx4 v[232:235], v[172:173] offset:256
	s_waitcnt vmcnt(0) lgkmcnt(0)
	v_lshlrev_b32_e32 v186, 16, v176
	v_and_b32_e32 v187, 0xffff0000, v176
	v_lshlrev_b32_e32 v198, 16, v177
	v_and_b32_e32 v199, 0xffff0000, v177
	v_lshlrev_b32_e32 v200, 16, v178
	v_and_b32_e32 v201, 0xffff0000, v178
	v_lshlrev_b32_e32 v202, 16, v179
	v_and_b32_e32 v203, 0xffff0000, v179
	v_mov_b64_e32 v[176:177], v[240:241]
	v_mov_b64_e32 v[178:179], v[242:243]
	v_mov_b64_e32 v[182:183], v[236:237]
	v_mov_b64_e32 v[184:185], v[238:239]
	s_waitcnt vmcnt(1)
	v_pk_fma_f32 v[120:121], v[120:121], v[178:179], v[202:203]
	v_mov_b64_e32 v[170:171], v[232:233]
	v_mov_b64_e32 v[172:173], v[234:235]
	s_waitcnt vmcnt(0)
	v_pk_fma_f32 v[116:117], v[116:117], v[184:185], v[198:199]
	v_pk_fma_f32 v[114:115], v[114:115], v[182:183], v[186:187]
	v_pk_fma_f32 v[118:119], v[118:119], v[176:177], v[200:201]
	s_waitcnt lgkmcnt(0)
	v_lshlrev_b32_e32 v182, 16, v170
	v_and_b32_e32 v183, 0xffff0000, v170
	v_lshlrev_b32_e32 v184, 16, v171
	v_and_b32_e32 v185, 0xffff0000, v171
	v_lshlrev_b32_e32 v186, 16, v172
	v_and_b32_e32 v187, 0xffff0000, v172
	v_lshlrev_b32_e32 v198, 16, v173
	v_and_b32_e32 v199, 0xffff0000, v173
	v_mov_b64_e32 v[170:171], v[248:249]
	v_mov_b64_e32 v[172:173], v[250:251]
	v_mov_b64_e32 v[176:177], v[244:245]
	v_mov_b64_e32 v[178:179], v[246:247]
	s_waitcnt vmcnt(1)
	v_pk_fma_f32 v[124:125], v[124:125], v[172:173], v[198:199]
	s_waitcnt vmcnt(0)
	v_pk_fma_f32 v[126:127], v[126:127], v[176:177], v[182:183]
	v_pk_fma_f32 v[128:129], v[128:129], v[178:179], v[184:185]
	v_mov_b32_e32 v172, v115
	v_mov_b32_e32 v173, v127
	v_pk_fma_f32 v[122:123], v[122:123], v[170:171], v[186:187]
	v_mov_b32_e32 v170, v114
	v_mov_b32_e32 v171, v126
	v_pk_mul_f32 v[172:173], v[172:173], v[172:173]
	v_mov_b32_e32 v176, v117
	v_mov_b32_e32 v177, v129
	v_pk_fma_f32 v[170:171], v[170:171], v[170:171], v[172:173]
	v_mov_b32_e32 v172, v116
	v_mov_b32_e32 v173, v128
	v_pk_mul_f32 v[176:177], v[176:177], v[176:177]
	v_mov_b32_e32 v178, v121
	v_pk_fma_f32 v[172:173], v[172:173], v[172:173], v[176:177]
	v_mov_b32_e32 v176, v119
	v_mov_b32_e32 v177, v123
	v_pk_add_f32 v[170:171], v[170:171], v[172:173]
	v_mov_b32_e32 v172, v118
	v_mov_b32_e32 v173, v122
	v_pk_mul_f32 v[176:177], v[176:177], v[176:177]
	v_mov_b32_e32 v179, v125
	v_pk_fma_f32 v[172:173], v[172:173], v[172:173], v[176:177]
	v_mov_b32_e32 v176, v120
	v_mov_b32_e32 v177, v124
	v_pk_mul_f32 v[178:179], v[178:179], v[178:179]
	s_nop 0
	v_pk_fma_f32 v[176:177], v[176:177], v[176:177], v[178:179]
	s_nop 0
	v_pk_add_f32 v[172:173], v[172:173], v[176:177]
	s_nop 0
	v_pk_add_f32 v[170:171], v[170:171], v[172:173]
	s_nop 0
	v_add_f32_e32 v198, v170, v171
	v_add_u32_e32 v170, 0x80, v146
	v_ashrrev_i32_e32 v171, 31, v170
	v_lshlrev_b64 v[172:173], 11, v[170:171]
	v_lshl_add_u64 v[172:173], v[164:165], 0, v[172:173]
	v_mov_b64_e32 v[176:177], v[172:173]
	flat_load_dwordx4 v[182:185], v[176:177]
	flat_load_dwordx4 v[232:235], v[176:177] offset:256
	s_waitcnt vmcnt(0) lgkmcnt(0)
	v_lshlrev_b32_e32 v178, 16, v182
	v_and_b32_e32 v179, 0xffff0000, v182
	v_lshlrev_b32_e32 v186, 16, v183
	v_and_b32_e32 v187, 0xffff0000, v183
	v_lshlrev_b32_e32 v204, 16, v184
	v_and_b32_e32 v205, 0xffff0000, v184
	v_lshlrev_b32_e32 v206, 16, v185
	v_and_b32_e32 v207, 0xffff0000, v185
	v_mov_b64_e32 v[182:183], v[240:241]
	v_mov_b64_e32 v[184:185], v[242:243]
	v_mov_b64_e32 v[200:201], v[236:237]
	v_mov_b64_e32 v[202:203], v[238:239]
	s_waitcnt vmcnt(1)
;     __device__ __forceinline__ void fused(f32x4 (&acc)[2][2][4][2], const Unit& u, int wr, int wc, int fr, int fq, LAS unsigned char* lds, int wid, int lane) const {
;     ...
; #pragma unroll
;             for (int m = 0; m < 4; ++m) {
;                 const bf16_t* hrow = hb + (size_t)(row0 + ai * HALF + m * 16) * DM + col0;
;                 asm volatile("" : "+v"(hrow) : "v"(dep));
;                 const float r1 = rv[ai][m];
;                 float q = 0.f;
; #pragma unroll
;                 for (int bj = 0; bj < 2; ++bj) {
;                     const u32x4 hv = *(const u32x4*)(hrow + bj * HALF);
;                     const f32x4 h0 = (f32x4){__uint_as_float(hv.x << 16), __uint_as_float(hv.x & 0xffff0000u), __uint_as_float(hv.y << 16), __uint_as_float(hv.y & 0xffff0000u)};
;                     const f32x4 h1 = (f32x4){__uint_as_float(hv.z << 16), __uint_as_float(hv.z & 0xffff0000u), __uint_as_float(hv.w << 16), __uint_as_float(hv.w & 0xffff0000u)};
;                     const f32x4 gg0 = *(const f32x4*)(gpost + col0 + bj * HALF), gg1 = *(const f32x4*)(gpost + col0 + bj * HALF + 4);
;                     f32x4 x0 = h0 + acc[ai][bj][m][0] * r1 * gg0, x1 = h1 + acc[ai][bj][m][1] * r1 * gg1;
;                     acc[ai][bj][m][0] = x0; acc[ai][bj][m][1] = x1;
;                     q += ((x0[0] * x0[0] + x0[1] * x0[1]) + (x0[2] * x0[2] + x0[3] * x0[3])) + ((x1[0] * x1[0] + x1[1] * x1[1]) + (x1[2] * x1[2] + x1[3] * x1[3]));
	v_pk_fma_f32 v[100:101], v[100:101], v[184:185], v[206:207]
	s_waitcnt vmcnt(0)
	v_pk_fma_f32 v[102:103], v[102:103], v[200:201], v[178:179]
	v_mov_b64_e32 v[176:177], v[232:233]
	v_mov_b64_e32 v[178:179], v[234:235]
	v_pk_fma_f32 v[104:105], v[104:105], v[202:203], v[186:187]
	v_pk_fma_f32 v[98:99], v[98:99], v[182:183], v[204:205]
	s_waitcnt vmcnt(0) lgkmcnt(0)
	v_lshlrev_b32_e32 v186, 16, v176
	v_and_b32_e32 v187, 0xffff0000, v176
	v_lshlrev_b32_e32 v200, 16, v177
	v_and_b32_e32 v201, 0xffff0000, v177
	v_lshlrev_b32_e32 v202, 16, v178
	v_and_b32_e32 v203, 0xffff0000, v178
	v_lshlrev_b32_e32 v204, 16, v179
	v_and_b32_e32 v205, 0xffff0000, v179
	v_mov_b64_e32 v[176:177], v[248:249]
	v_mov_b64_e32 v[178:179], v[250:251]
	v_mov_b64_e32 v[182:183], v[244:245]
	v_mov_b64_e32 v[184:185], v[246:247]
	s_waitcnt vmcnt(1)
	v_pk_fma_f32 v[84:85], v[84:85], v[178:179], v[204:205]
	s_waitcnt vmcnt(0)
	v_pk_fma_f32 v[86:87], v[86:87], v[182:183], v[186:187]
	v_pk_fma_f32 v[88:89], v[88:89], v[184:185], v[200:201]
	v_mov_b32_e32 v178, v103
	v_mov_b32_e32 v179, v87
	v_pk_fma_f32 v[82:83], v[82:83], v[176:177], v[202:203]
	v_mov_b32_e32 v176, v102
	v_mov_b32_e32 v177, v86
	v_pk_mul_f32 v[178:179], v[178:179], v[178:179]
	v_mov_b32_e32 v182, v105
	v_mov_b32_e32 v183, v89
	v_pk_fma_f32 v[176:177], v[176:177], v[176:177], v[178:179]
	v_mov_b32_e32 v178, v104
	v_mov_b32_e32 v179, v88
	v_pk_mul_f32 v[182:183], v[182:183], v[182:183]
	v_mov_b32_e32 v184, v101
	v_pk_fma_f32 v[178:179], v[178:179], v[178:179], v[182:183]
	v_mov_b32_e32 v182, v99
	v_mov_b32_e32 v183, v83
	v_pk_add_f32 v[176:177], v[176:177], v[178:179]
	v_mov_b32_e32 v178, v98
	v_mov_b32_e32 v179, v82
	v_pk_mul_f32 v[182:183], v[182:183], v[182:183]
	v_mov_b32_e32 v185, v85
	v_pk_fma_f32 v[178:179], v[178:179], v[178:179], v[182:183]
	v_mov_b32_e32 v182, v100
	v_mov_b32_e32 v183, v84
	v_pk_mul_f32 v[184:185], v[184:185], v[184:185]
	s_nop 0
	v_pk_fma_f32 v[182:183], v[182:183], v[182:183], v[184:185]
	s_nop 0
	v_pk_add_f32 v[178:179], v[178:179], v[182:183]
	s_nop 0
	v_pk_add_f32 v[176:177], v[176:177], v[178:179]
	s_nop 0
	v_add_f32_e32 v199, v176, v177
	v_add_u32_e32 v176, 0x90, v146
	v_ashrrev_i32_e32 v177, 31, v176
	v_lshlrev_b64 v[178:179], 11, v[176:177]
	v_lshl_add_u64 v[178:179], v[164:165], 0, v[178:179]
	v_mov_b64_e32 v[182:183], v[178:179]
	flat_load_dwordx4 v[184:187], v[182:183]
	flat_load_dwordx4 v[232:235], v[182:183] offset:256
	s_waitcnt vmcnt(0) lgkmcnt(0)
	v_lshlrev_b32_e32 v204, 16, v184
	v_and_b32_e32 v205, 0xffff0000, v184
	v_lshlrev_b32_e32 v206, 16, v185
	v_and_b32_e32 v207, 0xffff0000, v185
	v_lshlrev_b32_e32 v208, 16, v186
	v_and_b32_e32 v209, 0xffff0000, v186
	v_lshlrev_b32_e32 v210, 16, v187
	v_and_b32_e32 v211, 0xffff0000, v187
	v_mov_b64_e32 v[184:185], v[240:241]
	v_mov_b64_e32 v[186:187], v[242:243]
	v_mov_b64_e32 v[200:201], v[236:237]
	v_mov_b64_e32 v[202:203], v[238:239]
	s_waitcnt vmcnt(1)
	v_pk_fma_f32 v[66:67], v[66:67], v[184:185], v[208:209]
	v_mov_b64_e32 v[182:183], v[232:233]
	v_mov_b64_e32 v[184:185], v[234:235]
	s_waitcnt vmcnt(0)
	v_pk_fma_f32 v[72:73], v[72:73], v[202:203], v[206:207]
	v_pk_fma_f32 v[70:71], v[70:71], v[200:201], v[204:205]
	v_pk_fma_f32 v[68:69], v[68:69], v[186:187], v[210:211]
	v_mov_b32_e32 v174, v70
	s_waitcnt lgkmcnt(0)
	v_lshlrev_b32_e32 v186, 16, v182
	v_and_b32_e32 v187, 0xffff0000, v182
	v_lshlrev_b32_e32 v204, 16, v183
	v_and_b32_e32 v205, 0xffff0000, v183
	v_lshlrev_b32_e32 v206, 16, v184
	v_and_b32_e32 v207, 0xffff0000, v184
	v_lshlrev_b32_e32 v208, 16, v185
	v_and_b32_e32 v209, 0xffff0000, v185
	v_mov_b64_e32 v[182:183], v[248:249]
	v_mov_b64_e32 v[184:185], v[250:251]
	v_mov_b64_e32 v[200:201], v[244:245]
	v_mov_b64_e32 v[202:203], v[246:247]
	s_waitcnt vmcnt(1)
	v_pk_fma_f32 v[50:51], v[50:51], v[182:183], v[206:207]
	s_waitcnt vmcnt(0)
	v_pk_fma_f32 v[54:55], v[54:55], v[200:201], v[186:187]
	v_pk_fma_f32 v[56:57], v[56:57], v[202:203], v[204:205]
	v_mov_b32_e32 v182, v71
	v_mov_b32_e32 v183, v55
	v_pk_fma_f32 v[52:53], v[52:53], v[184:185], v[208:209]
	v_mov_b32_e32 v175, v54
	v_pk_mul_f32 v[182:183], v[182:183], v[182:183]
	v_mov_b32_e32 v184, v73
	v_mov_b32_e32 v185, v57
	v_pk_fma_f32 v[174:175], v[174:175], v[174:175], v[182:183]
	v_mov_b32_e32 v182, v72
	v_mov_b32_e32 v183, v56
	v_pk_mul_f32 v[184:185], v[184:185], v[184:185]
	v_mov_b32_e32 v186, v69
	v_pk_fma_f32 v[182:183], v[182:183], v[182:183], v[184:185]
	v_mov_b32_e32 v184, v67
	v_mov_b32_e32 v185, v51
	v_pk_add_f32 v[174:175], v[174:175], v[182:183]
	v_mov_b32_e32 v182, v66
	v_mov_b32_e32 v183, v50
	v_pk_mul_f32 v[184:185], v[184:185], v[184:185]
	v_mov_b32_e32 v187, v53
	v_pk_fma_f32 v[182:183], v[182:183], v[182:183], v[184:185]
	v_mov_b32_e32 v184, v68
	v_mov_b32_e32 v185, v52
	v_pk_mul_f32 v[186:187], v[186:187], v[186:187]
	s_nop 0
	v_pk_fma_f32 v[184:185], v[184:185], v[184:185], v[186:187]
	s_nop 0
	v_pk_add_f32 v[182:183], v[182:183], v[184:185]
	s_nop 0
	v_pk_add_f32 v[174:175], v[174:175], v[182:183]
	s_nop 0
	v_add_f32_e32 v200, v174, v175
	v_add_u32_e32 v174, 0xa0, v146
	v_ashrrev_i32_e32 v175, 31, v174
	v_lshlrev_b64 v[182:183], 11, v[174:175]
	v_lshl_add_u64 v[182:183], v[164:165], 0, v[182:183]
	v_mov_b64_e32 v[184:185], v[182:183]
	flat_load_dwordx4 v[202:205], v[184:185]
	flat_load_dwordx4 v[232:235], v[184:185] offset:256
	s_waitcnt vmcnt(0) lgkmcnt(0)
	v_lshlrev_b32_e32 v186, 16, v202
	v_and_b32_e32 v187, 0xffff0000, v202
	v_lshlrev_b32_e32 v210, 16, v203
	v_and_b32_e32 v211, 0xffff0000, v203
	v_lshlrev_b32_e32 v212, 16, v204
	v_and_b32_e32 v213, 0xffff0000, v204
	v_lshlrev_b32_e32 v214, 16, v205
	v_and_b32_e32 v215, 0xffff0000, v205
	v_mov_b64_e32 v[202:203], v[240:241]
	v_mov_b64_e32 v[204:205], v[242:243]
	v_mov_b64_e32 v[206:207], v[236:237]
	v_mov_b64_e32 v[208:209], v[238:239]
	s_waitcnt vmcnt(1)
;     __device__ __forceinline__ void fused(f32x4 (&acc)[2][2][4][2], const Unit& u, int wr, int wc, int fr, int fq, LAS unsigned char* lds, int wid, int lane) const {
;     ...
; #pragma unroll
;             for (int m = 0; m < 4; ++m) {
;                 const bf16_t* hrow = hb + (size_t)(row0 + ai * HALF + m * 16) * DM + col0;
;                 asm volatile("" : "+v"(hrow) : "v"(dep));
;                 const float r1 = rv[ai][m];
;                 float q = 0.f;
; #pragma unroll
;                 for (int bj = 0; bj < 2; ++bj) {
;                     const u32x4 hv = *(const u32x4*)(hrow + bj * HALF);
;                     const f32x4 h0 = (f32x4){__uint_as_float(hv.x << 16), __uint_as_float(hv.x & 0xffff0000u), __uint_as_float(hv.y << 16), __uint_as_float(hv.y & 0xffff0000u)};
;                     const f32x4 h1 = (f32x4){__uint_as_float(hv.z << 16), __uint_as_float(hv.z & 0xffff0000u), __uint_as_float(hv.w << 16), __uint_as_float(hv.w & 0xffff0000u)};
;                     const f32x4 gg0 = *(const f32x4*)(gpost + col0 + bj * HALF), gg1 = *(const f32x4*)(gpost + col0 + bj * HALF + 4);
;                     f32x4 x0 = h0 + acc[ai][bj][m][0] * r1 * gg0, x1 = h1 + acc[ai][bj][m][1] * r1 * gg1;
;                     acc[ai][bj][m][0] = x0; acc[ai][bj][m][1] = x1;
;                     q += ((x0[0] * x0[0] + x0[1] * x0[1]) + (x0[2] * x0[2] + x0[3] * x0[3])) + ((x1[0] * x1[0] + x1[1] * x1[1]) + (x1[2] * x1[2] + x1[3] * x1[3]));
;                 }
;                 sv[ai][m] = q;
;                 dep = q;
;             }
;         if (fout) {
; #pragma unroll
;             for (int ai = 0; ai < 2; ++ai)
; #pragma unroll
;                 for (int m = 0; m < 4; ++m) { float* orow = fout + (size_t)(row0 + ai * HALF + m * 16) * DM + col0;
; #pragma unroll
;                     for (int bj = 0; bj < 2; ++bj) { *(f32x4*)(orow + bj * HALF) = acc[ai][bj][m][0]; *(f32x4*)(orow + bj * HALF + 4) = acc[ai][bj][m][1]; } }
	v_pk_fma_f32 v[36:37], v[36:37], v[204:205], v[214:215]
	s_waitcnt vmcnt(0)
	v_pk_fma_f32 v[38:39], v[38:39], v[206:207], v[186:187]
	v_mov_b64_e32 v[184:185], v[232:233]
	v_mov_b64_e32 v[186:187], v[234:235]
	v_pk_fma_f32 v[40:41], v[40:41], v[208:209], v[210:211]
	v_pk_fma_f32 v[34:35], v[34:35], v[202:203], v[212:213]
	s_waitcnt vmcnt(0) lgkmcnt(0)
	v_lshlrev_b32_e32 v206, 16, v184
	v_and_b32_e32 v207, 0xffff0000, v184
	v_lshlrev_b32_e32 v208, 16, v185
	v_and_b32_e32 v209, 0xffff0000, v185
	v_lshlrev_b32_e32 v210, 16, v186
	v_and_b32_e32 v211, 0xffff0000, v186
	v_lshlrev_b32_e32 v212, 16, v187
	v_and_b32_e32 v213, 0xffff0000, v187
	v_mov_b64_e32 v[184:185], v[248:249]
	v_mov_b64_e32 v[186:187], v[250:251]
	v_mov_b64_e32 v[202:203], v[244:245]
	v_mov_b64_e32 v[204:205], v[246:247]
	s_waitcnt vmcnt(1)
	v_pk_fma_f32 v[20:21], v[20:21], v[186:187], v[212:213]
	s_waitcnt vmcnt(0)
	v_pk_fma_f32 v[22:23], v[22:23], v[202:203], v[206:207]
	v_pk_fma_f32 v[24:25], v[24:25], v[204:205], v[208:209]
	v_mov_b32_e32 v186, v39
	v_mov_b32_e32 v187, v23
	v_pk_fma_f32 v[18:19], v[18:19], v[184:185], v[210:211]
	v_mov_b32_e32 v184, v38
	v_mov_b32_e32 v185, v22
	v_pk_mul_f32 v[186:187], v[186:187], v[186:187]
	v_mov_b32_e32 v202, v41
	v_mov_b32_e32 v203, v25
	v_pk_fma_f32 v[184:185], v[184:185], v[184:185], v[186:187]
	v_mov_b32_e32 v186, v40
	v_mov_b32_e32 v187, v24
	v_pk_mul_f32 v[202:203], v[202:203], v[202:203]
	v_mov_b32_e32 v204, v37
	v_pk_fma_f32 v[186:187], v[186:187], v[186:187], v[202:203]
	v_mov_b32_e32 v202, v35
	v_mov_b32_e32 v203, v19
	v_pk_add_f32 v[184:185], v[184:185], v[186:187]
	v_mov_b32_e32 v186, v34
	v_mov_b32_e32 v187, v18
	v_pk_mul_f32 v[202:203], v[202:203], v[202:203]
	v_mov_b32_e32 v205, v21
	v_pk_fma_f32 v[186:187], v[186:187], v[186:187], v[202:203]
	v_mov_b32_e32 v202, v36
	v_mov_b32_e32 v203, v20
	v_pk_mul_f32 v[204:205], v[204:205], v[204:205]
	s_nop 0
	v_pk_fma_f32 v[202:203], v[202:203], v[202:203], v[204:205]
	s_nop 0
	v_pk_add_f32 v[186:187], v[186:187], v[202:203]
	s_nop 0
	v_pk_add_f32 v[184:185], v[184:185], v[186:187]
	s_nop 0
	v_add_f32_e32 v158, v184, v185
	v_add_u32_e32 v184, 0xb0, v146
	v_ashrrev_i32_e32 v185, 31, v184
	v_lshlrev_b64 v[186:187], 11, v[184:185]
	v_lshl_add_u64 v[164:165], v[164:165], 0, v[186:187]
	v_mov_b64_e32 v[186:187], v[164:165]
	flat_load_dwordx4 v[202:205], v[186:187]
	flat_load_dwordx4 v[232:235], v[186:187] offset:256
	s_waitcnt vmcnt(0) lgkmcnt(0)
	v_lshlrev_b32_e32 v210, 16, v202
	v_and_b32_e32 v211, 0xffff0000, v202
	v_lshlrev_b32_e32 v212, 16, v203
	v_and_b32_e32 v213, 0xffff0000, v203
	v_lshlrev_b32_e32 v214, 16, v204
	v_and_b32_e32 v215, 0xffff0000, v204
	v_lshlrev_b32_e32 v216, 16, v205
	v_and_b32_e32 v217, 0xffff0000, v205
	v_mov_b64_e32 v[202:203], v[240:241]
	v_mov_b64_e32 v[204:205], v[242:243]
	v_mov_b64_e32 v[206:207], v[236:237]
	v_mov_b64_e32 v[208:209], v[238:239]
	s_waitcnt vmcnt(1)
	v_pk_fma_f32 v[12:13], v[12:13], v[204:205], v[216:217]
	v_pk_fma_f32 v[10:11], v[10:11], v[202:203], v[214:215]
	v_mov_b64_e32 v[202:203], v[232:233]
	v_mov_b64_e32 v[204:205], v[234:235]
	s_waitcnt vmcnt(0)
	v_pk_fma_f32 v[16:17], v[16:17], v[208:209], v[212:213]
	v_pk_fma_f32 v[14:15], v[14:15], v[206:207], v[210:211]
	s_waitcnt lgkmcnt(0)
	v_lshlrev_b32_e32 v186, 16, v202
	v_and_b32_e32 v187, 0xffff0000, v202
	v_lshlrev_b32_e32 v210, 16, v203
	v_and_b32_e32 v211, 0xffff0000, v203
	v_lshlrev_b32_e32 v212, 16, v204
	v_and_b32_e32 v213, 0xffff0000, v204
	v_lshlrev_b32_e32 v214, 16, v205
	v_and_b32_e32 v215, 0xffff0000, v205
	v_mov_b64_e32 v[202:203], v[248:249]
	v_mov_b64_e32 v[204:205], v[250:251]
	v_mov_b64_e32 v[206:207], v[244:245]
	v_mov_b64_e32 v[208:209], v[246:247]
	s_waitcnt vmcnt(1)
	v_pk_fma_f32 v[4:5], v[4:5], v[204:205], v[214:215]
	s_waitcnt vmcnt(0)
	v_pk_fma_f32 v[8:9], v[8:9], v[208:209], v[210:211]
	v_pk_fma_f32 v[6:7], v[6:7], v[206:207], v[186:187]
	v_pk_fma_f32 v[2:3], v[2:3], v[202:203], v[212:213]
	s_cbranch_vccnz .LBB0_1700
	v_lshlrev_b64 v[156:157], 12, v[146:147]
	v_lshl_add_u64 v[156:157], s[14:15], 0, v[156:157]
	v_lshlrev_b64 v[154:155], 2, v[154:155]
	v_lshl_add_u64 v[156:157], v[156:157], 0, v[154:155]
	global_store_dwordx4 v[156:157], v[26:29], off
	global_store_dwordx4 v[156:157], v[30:33], off offset:16
	global_store_dwordx4 v[156:157], v[42:45], off offset:512
	global_store_dwordx4 v[156:157], v[46:49], off offset:528
	v_lshlrev_b64 v[156:157], 12, v[150:151]
	v_lshl_add_u64 v[156:157], s[14:15], 0, v[156:157]
	v_lshl_add_u64 v[156:157], v[156:157], 0, v[154:155]
	global_store_dwordx4 v[156:157], v[58:61], off
	global_store_dwordx4 v[156:157], v[62:65], off offset:16
	global_store_dwordx4 v[156:157], v[74:77], off offset:512
	global_store_dwordx4 v[156:157], v[78:81], off offset:528
	v_lshlrev_b64 v[156:157], 12, v[160:161]
	v_lshl_add_u64 v[156:157], s[14:15], 0, v[156:157]
	v_lshl_add_u64 v[156:157], v[156:157], 0, v[154:155]
	global_store_dwordx4 v[156:157], v[90:93], off
	global_store_dwordx4 v[156:157], v[94:97], off offset:16
	global_store_dwordx4 v[156:157], v[106:109], off offset:512
	global_store_dwordx4 v[156:157], v[110:113], off offset:528
	v_lshlrev_b64 v[156:157], 12, v[166:167]
	v_lshl_add_u64 v[156:157], s[14:15], 0, v[156:157]
	v_lshl_add_u64 v[156:157], v[156:157], 0, v[154:155]
	global_store_dwordx4 v[156:157], v[114:117], off
	global_store_dwordx4 v[156:157], v[118:121], off offset:16
	global_store_dwordx4 v[156:157], v[126:129], off offset:512
	global_store_dwordx4 v[156:157], v[122:125], off offset:528
	v_lshlrev_b64 v[156:157], 12, v[170:171]
	v_lshl_add_u64 v[156:157], s[14:15], 0, v[156:157]
	v_lshl_add_u64 v[156:157], v[156:157], 0, v[154:155]
	global_store_dwordx4 v[156:157], v[102:105], off
	global_store_dwordx4 v[156:157], v[98:101], off offset:16
	global_store_dwordx4 v[156:157], v[86:89], off offset:512
	global_store_dwordx4 v[156:157], v[82:85], off offset:528
	v_lshlrev_b64 v[156:157], 12, v[176:177]
	v_lshl_add_u64 v[156:157], s[14:15], 0, v[156:157]
	v_lshl_add_u64 v[156:157], v[156:157], 0, v[154:155]
	global_store_dwordx4 v[156:157], v[70:73], off
	global_store_dwordx4 v[156:157], v[66:69], off offset:16
	global_store_dwordx4 v[156:157], v[54:57], off offset:512
	global_store_dwordx4 v[156:157], v[50:53], off offset:528
	v_lshlrev_b64 v[156:157], 12, v[174:175]
	v_lshl_add_u64 v[156:157], s[14:15], 0, v[156:157]
	v_lshl_add_u64 v[156:157], v[156:157], 0, v[154:155]
	global_store_dwordx4 v[156:157], v[38:41], off
	global_store_dwordx4 v[156:157], v[34:37], off offset:16
	global_store_dwordx4 v[156:157], v[22:25], off offset:512
	global_store_dwordx4 v[156:157], v[18:21], off offset:528
	v_lshlrev_b64 v[156:157], 12, v[184:185]
	v_lshl_add_u64 v[156:157], s[14:15], 0, v[156:157]
	v_lshl_add_u64 v[154:155], v[156:157], 0, v[154:155]
	global_store_dwordx4 v[154:155], v[14:17], off
	global_store_dwordx4 v[154:155], v[10:13], off offset:16
	global_store_dwordx4 v[154:155], v[6:9], off offset:512
	global_store_dwordx4 v[154:155], v[2:5], off offset:528
	s_cbranch_execnz .LBB0_1701
